# barrier leader skips the XCD L2 writeback (buffer_wbl2) when all workgroups of that barrier sit on one XCD (nx<=1); multi-XCD barriers unchanged; on top of the aligned version
# speedup vs baseline: 1.0016x; 1.0000x over previous
; __device__ __forceinline__ unsigned xb_ld(unsigned* p)              { return __hip_atomic_load((GAS unsigned*)p, __ATOMIC_RELAXED, __HIP_MEMORY_SCOPE_AGENT); }
; __device__ __forceinline__ unsigned xb_add(unsigned* p, unsigned v) { return __hip_atomic_fetch_add((GAS unsigned*)p, v, __ATOMIC_RELAXED, __HIP_MEMORY_SCOPE_AGENT); }
; #define XB_SPIN(cond, bar) do { unsigned _sp = 0; while (cond) { __builtin_amdgcn_s_sleep(1); \
;     if ((++_sp & 255u) == 0u) { if (xb_ld(&(bar)[XB_TMO])) break; if (_sp > XB_SPIN_CAP) { xb_add(&(bar)[XB_TMO], 1u); break; } } } } while (0)
; __device__ __forceinline__ void xcd_barrier(const XcdBarrier& b) {
;     ...
;         if (old + 1u == (gen + 1u) * nloc) {
;             __builtin_amdgcn_fence(__ATOMIC_RELEASE, "agent");
;             asm volatile("s_waitcnt vmcnt(0)" ::: "memory");
;             if (nx > 1u) {
;             const unsigned og = xb_add(&bar[XB_TOP], 1u);
;             const unsigned tg = og / nx;
;             if (og + 1u == (tg + 1u) * nx) xb_add(&bar[XB_TOPGEN], 1u);
;             else XB_SPIN(xb_ld(&bar[XB_TOPGEN]) == tg, bar);
;             }
;             __builtin_amdgcn_fence(__ATOMIC_ACQUIRE, "agent");
;             xb_add(&bar[XB_XGEN(b.x)], 1u);
;             asm volatile("s_waitcnt vmcnt(0)" ::: "memory");
.LBB0_86:
	s_andn2_saveexec_b64 s[4:5], s[4:5]
	s_cbranch_execz .LBB0_108
	s_waitcnt lgkmcnt(0)
	v_cmp_gt_u32_e32 vcc, 2, v1
	s_cbranch_vccnz .Lnowb_0
	buffer_wbl2 sc1
.Lnowb_0:
	s_waitcnt vmcnt(0)
	s_cbranch_vccnz .LBB0_105
	s_mov_b64 s[6:7], exec
	v_mbcnt_lo_u32_b32 v2, s6, 0
	v_mbcnt_hi_u32_b32 v2, s7, v2
	v_cmp_eq_u32_e32 vcc, 0, v2
	s_and_saveexec_b64 s[4:5], vcc
	s_cbranch_execz .LBB0_90
	s_bcnt1_i32_b64 s6, s[6:7]
	v_mov_b32_e32 v3, 0x7000
	v_mov_b32_e32 v4, s6
	global_atomic_add v3, v3, v4, s[8:9] offset:1024 sc0

; __device__ __forceinline__ unsigned xb_ld(unsigned* p)              { return __hip_atomic_load((GAS unsigned*)p, __ATOMIC_RELAXED, __HIP_MEMORY_SCOPE_AGENT); }
; __device__ __forceinline__ unsigned xb_add(unsigned* p, unsigned v) { return __hip_atomic_fetch_add((GAS unsigned*)p, v, __ATOMIC_RELAXED, __HIP_MEMORY_SCOPE_AGENT); }
; #define XB_SPIN(cond, bar) do { unsigned _sp = 0; while (cond) { __builtin_amdgcn_s_sleep(1); \
;     if ((++_sp & 255u) == 0u) { if (xb_ld(&(bar)[XB_TMO])) break; if (_sp > XB_SPIN_CAP) { xb_add(&(bar)[XB_TMO], 1u); break; } } } } while (0)
; __device__ __forceinline__ void xcd_barrier(const XcdBarrier& b) {
;     ...
;         if (old + 1u == (gen + 1u) * nloc) {
;             __builtin_amdgcn_fence(__ATOMIC_RELEASE, "agent");
;             asm volatile("s_waitcnt vmcnt(0)" ::: "memory");
;             if (nx > 1u) {
;             const unsigned og = xb_add(&bar[XB_TOP], 1u);
;             const unsigned tg = og / nx;
;             if (og + 1u == (tg + 1u) * nx) xb_add(&bar[XB_TOPGEN], 1u);
;             else XB_SPIN(xb_ld(&bar[XB_TOPGEN]) == tg, bar);
;             }
;             __builtin_amdgcn_fence(__ATOMIC_ACQUIRE, "agent");
;             xb_add(&bar[XB_XGEN(b.x)], 1u);
;             asm volatile("s_waitcnt vmcnt(0)" ::: "memory");
.LBB0_189:
	s_andn2_saveexec_b64 s[2:3], s[2:3]
	s_cbranch_execz .LBB0_211
	s_waitcnt lgkmcnt(0)
	v_cmp_gt_u32_e32 vcc, 2, v1
	s_cbranch_vccnz .Lnowb_1
	buffer_wbl2 sc1
.Lnowb_1:
	s_waitcnt vmcnt(0)
	s_cbranch_vccnz .LBB0_208
	s_mov_b64 s[4:5], exec
	v_mbcnt_lo_u32_b32 v2, s4, 0
	v_mbcnt_hi_u32_b32 v2, s5, v2
	v_cmp_eq_u32_e32 vcc, 0, v2
	s_and_saveexec_b64 s[2:3], vcc
	s_cbranch_execz .LBB0_193
	s_bcnt1_i32_b64 s4, s[4:5]
	v_mov_b32_e32 v3, 0x7000
	v_mov_b32_e32 v4, s4
	global_atomic_add v3, v3, v4, s[8:9] offset:1024 sc0

; __device__ __forceinline__ unsigned xb_ld(unsigned* p)              { return __hip_atomic_load((GAS unsigned*)p, __ATOMIC_RELAXED, __HIP_MEMORY_SCOPE_AGENT); }
; __device__ __forceinline__ unsigned xb_add(unsigned* p, unsigned v) { return __hip_atomic_fetch_add((GAS unsigned*)p, v, __ATOMIC_RELAXED, __HIP_MEMORY_SCOPE_AGENT); }
; #define XB_SPIN(cond, bar) do { unsigned _sp = 0; while (cond) { __builtin_amdgcn_s_sleep(1); \
;     if ((++_sp & 255u) == 0u) { if (xb_ld(&(bar)[XB_TMO])) break; if (_sp > XB_SPIN_CAP) { xb_add(&(bar)[XB_TMO], 1u); break; } } } } while (0)
; __device__ __forceinline__ void xcd_barrier(const XcdBarrier& b) {
;     ...
;         if (old + 1u == (gen + 1u) * nloc) {
;             __builtin_amdgcn_fence(__ATOMIC_RELEASE, "agent");
;             asm volatile("s_waitcnt vmcnt(0)" ::: "memory");
;             if (nx > 1u) {
;             const unsigned og = xb_add(&bar[XB_TOP], 1u);
;             const unsigned tg = og / nx;
;             if (og + 1u == (tg + 1u) * nx) xb_add(&bar[XB_TOPGEN], 1u);
;             else XB_SPIN(xb_ld(&bar[XB_TOPGEN]) == tg, bar);
;             }
;             __builtin_amdgcn_fence(__ATOMIC_ACQUIRE, "agent");
;             xb_add(&bar[XB_XGEN(b.x)], 1u);
;             asm volatile("s_waitcnt vmcnt(0)" ::: "memory");
.LBB0_284:
	s_andn2_saveexec_b64 s[12:13], s[12:13]
	s_cbranch_execz .LBB0_306
	s_waitcnt lgkmcnt(0)
	v_cmp_gt_u32_e32 vcc, 2, v2
	s_cbranch_vccnz .Lnowb_2
	buffer_wbl2 sc1
.Lnowb_2:
	s_waitcnt vmcnt(0)
	s_cbranch_vccnz .LBB0_303
	s_mov_b64 s[14:15], exec
	v_mbcnt_lo_u32_b32 v3, s14, 0
	v_mbcnt_hi_u32_b32 v3, s15, v3
	v_cmp_eq_u32_e32 vcc, 0, v3
	s_and_saveexec_b64 s[12:13], vcc
	s_cbranch_execz .LBB0_288
	s_bcnt1_i32_b64 s14, s[14:15]
	v_mov_b32_e32 v4, s14
	v_mov_b32_e32 v5, 0x7000
	global_atomic_add v4, v5, v4, s[6:7] offset:1024 sc0

; __device__ __forceinline__ unsigned xb_ld(unsigned* p)              { return __hip_atomic_load((GAS unsigned*)p, __ATOMIC_RELAXED, __HIP_MEMORY_SCOPE_AGENT); }
; __device__ __forceinline__ unsigned xb_add(unsigned* p, unsigned v) { return __hip_atomic_fetch_add((GAS unsigned*)p, v, __ATOMIC_RELAXED, __HIP_MEMORY_SCOPE_AGENT); }
; #define XB_SPIN(cond, bar) do { unsigned _sp = 0; while (cond) { __builtin_amdgcn_s_sleep(1); \
;     if ((++_sp & 255u) == 0u) { if (xb_ld(&(bar)[XB_TMO])) break; if (_sp > XB_SPIN_CAP) { xb_add(&(bar)[XB_TMO], 1u); break; } } } } while (0)
; __device__ __forceinline__ void xcd_barrier(const XcdBarrier& b) {
;     ...
;         if (old + 1u == (gen + 1u) * nloc) {
;             __builtin_amdgcn_fence(__ATOMIC_RELEASE, "agent");
;             asm volatile("s_waitcnt vmcnt(0)" ::: "memory");
;             if (nx > 1u) {
;             const unsigned og = xb_add(&bar[XB_TOP], 1u);
;             const unsigned tg = og / nx;
;             if (og + 1u == (tg + 1u) * nx) xb_add(&bar[XB_TOPGEN], 1u);
;             else XB_SPIN(xb_ld(&bar[XB_TOPGEN]) == tg, bar);
;             }
;             __builtin_amdgcn_fence(__ATOMIC_ACQUIRE, "agent");
;             xb_add(&bar[XB_XGEN(b.x)], 1u);
;             asm volatile("s_waitcnt vmcnt(0)" ::: "memory");
.LBB0_341:
	s_andn2_saveexec_b64 s[14:15], s[14:15]
	s_cbranch_execz .LBB0_363
	s_waitcnt lgkmcnt(0)
	v_cmp_gt_u32_e32 vcc, 2, v2
	s_cbranch_vccnz .Lnowb_3
	buffer_wbl2 sc1
.Lnowb_3:
	s_waitcnt vmcnt(0)
	s_cbranch_vccnz .LBB0_360
	s_mov_b64 s[40:41], exec
	v_mbcnt_lo_u32_b32 v3, s40, 0
	v_mbcnt_hi_u32_b32 v3, s41, v3
	v_cmp_eq_u32_e32 vcc, 0, v3
	s_and_saveexec_b64 s[14:15], vcc
	s_cbranch_execz .LBB0_345
	s_bcnt1_i32_b64 s18, s[40:41]
	v_mov_b32_e32 v4, s18
	v_mov_b32_e32 v5, 0xa000
	global_atomic_add v4, v5, v4, s[12:13] offset:2560 sc0

; __device__ __forceinline__ unsigned xb_ld(unsigned* p)              { return __hip_atomic_load((GAS unsigned*)p, __ATOMIC_RELAXED, __HIP_MEMORY_SCOPE_AGENT); }
; __device__ __forceinline__ unsigned xb_add(unsigned* p, unsigned v) { return __hip_atomic_fetch_add((GAS unsigned*)p, v, __ATOMIC_RELAXED, __HIP_MEMORY_SCOPE_AGENT); }
; #define XB_SPIN(cond, bar) do { unsigned _sp = 0; while (cond) { __builtin_amdgcn_s_sleep(1); \
;     if ((++_sp & 255u) == 0u) { if (xb_ld(&(bar)[XB_TMO])) break; if (_sp > XB_SPIN_CAP) { xb_add(&(bar)[XB_TMO], 1u); break; } } } } while (0)
; __device__ __forceinline__ void xcd_barrier(const XcdBarrier& b) {
;     ...
;         if (old + 1u == (gen + 1u) * nloc) {
;             __builtin_amdgcn_fence(__ATOMIC_RELEASE, "agent");
;             asm volatile("s_waitcnt vmcnt(0)" ::: "memory");
;             if (nx > 1u) {
;             const unsigned og = xb_add(&bar[XB_TOP], 1u);
;             const unsigned tg = og / nx;
;             if (og + 1u == (tg + 1u) * nx) xb_add(&bar[XB_TOPGEN], 1u);
;             else XB_SPIN(xb_ld(&bar[XB_TOPGEN]) == tg, bar);
;             }
;             __builtin_amdgcn_fence(__ATOMIC_ACQUIRE, "agent");
;             xb_add(&bar[XB_XGEN(b.x)], 1u);
;             asm volatile("s_waitcnt vmcnt(0)" ::: "memory");
.LBB0_678:
	s_andn2_saveexec_b64 s[8:9], s[8:9]
	s_cbranch_execz .LBB0_758
	s_waitcnt lgkmcnt(0)
	v_cmp_gt_u32_e32 vcc, 2, v2
	s_cbranch_vccnz .Lnowb_7
	buffer_wbl2 sc1
.Lnowb_7:
	s_waitcnt vmcnt(0)
	s_cbranch_vccnz .LBB0_755
	s_mov_b64 s[10:11], exec
	v_mbcnt_lo_u32_b32 v1, s10, 0
	v_mbcnt_hi_u32_b32 v1, s11, v1
	v_cmp_eq_u32_e32 vcc, 0, v1
	s_and_saveexec_b64 s[8:9], vcc
	s_cbranch_execz .LBB0_682
	s_bcnt1_i32_b64 s10, s[10:11]
	v_mov_b32_e32 v3, s10
	v_mov_b32_e32 v4, 0x7000
	global_atomic_add v3, v4, v3, s[4:5] offset:1024 sc0

; __device__ __forceinline__ unsigned xb_ld(unsigned* p)              { return __hip_atomic_load((GAS unsigned*)p, __ATOMIC_RELAXED, __HIP_MEMORY_SCOPE_AGENT); }
; __device__ __forceinline__ unsigned xb_add(unsigned* p, unsigned v) { return __hip_atomic_fetch_add((GAS unsigned*)p, v, __ATOMIC_RELAXED, __HIP_MEMORY_SCOPE_AGENT); }
; #define XB_SPIN(cond, bar) do { unsigned _sp = 0; while (cond) { __builtin_amdgcn_s_sleep(1); \
;     if ((++_sp & 255u) == 0u) { if (xb_ld(&(bar)[XB_TMO])) break; if (_sp > XB_SPIN_CAP) { xb_add(&(bar)[XB_TMO], 1u); break; } } } } while (0)
; __device__ __forceinline__ void xcd_barrier(const XcdBarrier& b) {
;     ...
;         if (old + 1u == (gen + 1u) * nloc) {
;             __builtin_amdgcn_fence(__ATOMIC_RELEASE, "agent");
;             asm volatile("s_waitcnt vmcnt(0)" ::: "memory");
;             if (nx > 1u) {
;             const unsigned og = xb_add(&bar[XB_TOP], 1u);
;             const unsigned tg = og / nx;
;             if (og + 1u == (tg + 1u) * nx) xb_add(&bar[XB_TOPGEN], 1u);
;             else XB_SPIN(xb_ld(&bar[XB_TOPGEN]) == tg, bar);
;             }
;             __builtin_amdgcn_fence(__ATOMIC_ACQUIRE, "agent");
;             xb_add(&bar[XB_XGEN(b.x)], 1u);
;             asm volatile("s_waitcnt vmcnt(0)" ::: "memory");
.Lnowb_8:
	s_waitcnt vmcnt(0)
	s_cbranch_vccnz .LBB0_812
	s_mov_b64 s[40:41], exec
	v_mbcnt_lo_u32_b32 v3, s40, 0
	v_mbcnt_hi_u32_b32 v3, s41, v3
	v_cmp_eq_u32_e32 vcc, 0, v3
	s_and_saveexec_b64 s[14:15], vcc
	s_cbranch_execz .LBB0_740
	s_bcnt1_i32_b64 s3, s[40:41]
	v_mov_b32_e32 v4, s3
	v_mov_b32_e32 v5, 0xa000
	global_atomic_add v4, v5, v4, s[12:13] offset:2560 sc0

; __device__ __forceinline__ unsigned xb_ld(unsigned* p)              { return __hip_atomic_load((GAS unsigned*)p, __ATOMIC_RELAXED, __HIP_MEMORY_SCOPE_AGENT); }
; __device__ __forceinline__ unsigned xb_add(unsigned* p, unsigned v) { return __hip_atomic_fetch_add((GAS unsigned*)p, v, __ATOMIC_RELAXED, __HIP_MEMORY_SCOPE_AGENT); }
; #define XB_SPIN(cond, bar) do { unsigned _sp = 0; while (cond) { __builtin_amdgcn_s_sleep(1); \
;     if ((++_sp & 255u) == 0u) { if (xb_ld(&(bar)[XB_TMO])) break; if (_sp > XB_SPIN_CAP) { xb_add(&(bar)[XB_TMO], 1u); break; } } } } while (0)
; __device__ __forceinline__ void xcd_barrier(const XcdBarrier& b) {
;     ...
;         if (old + 1u == (gen + 1u) * nloc) {
;             __builtin_amdgcn_fence(__ATOMIC_RELEASE, "agent");
;             asm volatile("s_waitcnt vmcnt(0)" ::: "memory");
;             if (nx > 1u) {
;             const unsigned og = xb_add(&bar[XB_TOP], 1u);
;             const unsigned tg = og / nx;
;             if (og + 1u == (tg + 1u) * nx) xb_add(&bar[XB_TOPGEN], 1u);
;             else XB_SPIN(xb_ld(&bar[XB_TOPGEN]) == tg, bar);
;             }
;             __builtin_amdgcn_fence(__ATOMIC_ACQUIRE, "agent");
;             xb_add(&bar[XB_XGEN(b.x)], 1u);
;             asm volatile("s_waitcnt vmcnt(0)" ::: "memory");
.LBB0_793:
	s_andn2_saveexec_b64 s[10:11], s[10:11]
	s_cbranch_execz .LBB0_826
	s_waitcnt lgkmcnt(0)
	v_cmp_gt_u32_e32 vcc, 2, v2
	s_cbranch_vccnz .Lnowb_9
	buffer_wbl2 sc1
.Lnowb_9:
	s_waitcnt vmcnt(0)
	s_cbranch_vccnz .LBB0_823
	s_mov_b64 s[12:13], exec
	v_mbcnt_lo_u32_b32 v1, s12, 0
	v_mbcnt_hi_u32_b32 v1, s13, v1
	v_cmp_eq_u32_e32 vcc, 0, v1
	s_and_saveexec_b64 s[10:11], vcc
	s_cbranch_execz .LBB0_797
	s_bcnt1_i32_b64 s12, s[12:13]
	v_mov_b32_e32 v3, s12
	v_mov_b32_e32 v4, 0xa000
	global_atomic_add v3, v4, v3, s[8:9] offset:2560 sc0

; __device__ __forceinline__ unsigned xb_ld(unsigned* p)              { return __hip_atomic_load((GAS unsigned*)p, __ATOMIC_RELAXED, __HIP_MEMORY_SCOPE_AGENT); }
; __device__ __forceinline__ unsigned xb_add(unsigned* p, unsigned v) { return __hip_atomic_fetch_add((GAS unsigned*)p, v, __ATOMIC_RELAXED, __HIP_MEMORY_SCOPE_AGENT); }
; #define XB_SPIN(cond, bar) do { unsigned _sp = 0; while (cond) { __builtin_amdgcn_s_sleep(1); \
;     if ((++_sp & 255u) == 0u) { if (xb_ld(&(bar)[XB_TMO])) break; if (_sp > XB_SPIN_CAP) { xb_add(&(bar)[XB_TMO], 1u); break; } } } } while (0)
; __device__ __forceinline__ void xcd_barrier(const XcdBarrier& b) {
;     ...
;         if (old + 1u == (gen + 1u) * nloc) {
;             __builtin_amdgcn_fence(__ATOMIC_RELEASE, "agent");
;             asm volatile("s_waitcnt vmcnt(0)" ::: "memory");
;             if (nx > 1u) {
;             const unsigned og = xb_add(&bar[XB_TOP], 1u);
;             const unsigned tg = og / nx;
;             if (og + 1u == (tg + 1u) * nx) xb_add(&bar[XB_TOPGEN], 1u);
;             else XB_SPIN(xb_ld(&bar[XB_TOPGEN]) == tg, bar);
;             }
;             __builtin_amdgcn_fence(__ATOMIC_ACQUIRE, "agent");
;             xb_add(&bar[XB_XGEN(b.x)], 1u);
;             asm volatile("s_waitcnt vmcnt(0)" ::: "memory");
.Lnowb_10:
	s_waitcnt vmcnt(0)
	s_cbranch_vccnz .LBB0_892
	s_mov_b64 s[10:11], exec
	v_mbcnt_lo_u32_b32 v1, s10, 0
	v_mbcnt_hi_u32_b32 v1, s11, v1
	v_cmp_eq_u32_e32 vcc, 0, v1
	s_and_saveexec_b64 s[8:9], vcc
	s_cbranch_execz .LBB0_877
	s_bcnt1_i32_b64 s10, s[10:11]
	v_mov_b32_e32 v3, s10
	v_mov_b32_e32 v4, 0x7000
	global_atomic_add v3, v4, v3, s[2:3] offset:1024 sc0

; __device__ __forceinline__ unsigned xb_ld(unsigned* p)              { return __hip_atomic_load((GAS unsigned*)p, __ATOMIC_RELAXED, __HIP_MEMORY_SCOPE_AGENT); }
; __device__ __forceinline__ unsigned xb_add(unsigned* p, unsigned v) { return __hip_atomic_fetch_add((GAS unsigned*)p, v, __ATOMIC_RELAXED, __HIP_MEMORY_SCOPE_AGENT); }
; #define XB_SPIN(cond, bar) do { unsigned _sp = 0; while (cond) { __builtin_amdgcn_s_sleep(1); \
;     if ((++_sp & 255u) == 0u) { if (xb_ld(&(bar)[XB_TMO])) break; if (_sp > XB_SPIN_CAP) { xb_add(&(bar)[XB_TMO], 1u); break; } } } } while (0)
; __device__ __forceinline__ void xcd_barrier(const XcdBarrier& b) {
;     ...
;         if (old + 1u == (gen + 1u) * nloc) {
;             __builtin_amdgcn_fence(__ATOMIC_RELEASE, "agent");
;             asm volatile("s_waitcnt vmcnt(0)" ::: "memory");
;             if (nx > 1u) {
;             const unsigned og = xb_add(&bar[XB_TOP], 1u);
;             const unsigned tg = og / nx;
;             if (og + 1u == (tg + 1u) * nx) xb_add(&bar[XB_TOPGEN], 1u);
;             else XB_SPIN(xb_ld(&bar[XB_TOPGEN]) == tg, bar);
;             }
;             __builtin_amdgcn_fence(__ATOMIC_ACQUIRE, "agent");
;             xb_add(&bar[XB_XGEN(b.x)], 1u);
;             asm volatile("s_waitcnt vmcnt(0)" ::: "memory");
.LBB0_1225:
	s_andn2_saveexec_b64 s[6:7], s[6:7]
	s_cbranch_execz .LBB0_1247
	s_waitcnt lgkmcnt(0)
	v_cmp_gt_u32_e32 vcc, 2, v2
	s_cbranch_vccnz .Lnowb_14
	buffer_wbl2 sc1
.Lnowb_14:
	s_waitcnt vmcnt(0)
	s_cbranch_vccnz .LBB0_1244
	s_mov_b64 s[8:9], exec
	v_mbcnt_lo_u32_b32 v1, s8, 0
	v_mbcnt_hi_u32_b32 v1, s9, v1
	v_cmp_eq_u32_e32 vcc, 0, v1
	s_and_saveexec_b64 s[6:7], vcc
	s_cbranch_execz .LBB0_1229
	s_bcnt1_i32_b64 s8, s[8:9]
	v_mov_b32_e32 v3, s8
	v_mov_b32_e32 v4, 0x7000
	global_atomic_add v3, v4, v3, s[2:3] offset:1024 sc0

; __device__ __forceinline__ unsigned xb_ld(unsigned* p)              { return __hip_atomic_load((GAS unsigned*)p, __ATOMIC_RELAXED, __HIP_MEMORY_SCOPE_AGENT); }
; __device__ __forceinline__ unsigned xb_add(unsigned* p, unsigned v) { return __hip_atomic_fetch_add((GAS unsigned*)p, v, __ATOMIC_RELAXED, __HIP_MEMORY_SCOPE_AGENT); }
; #define XB_SPIN(cond, bar) do { unsigned _sp = 0; while (cond) { __builtin_amdgcn_s_sleep(1); \
;     if ((++_sp & 255u) == 0u) { if (xb_ld(&(bar)[XB_TMO])) break; if (_sp > XB_SPIN_CAP) { xb_add(&(bar)[XB_TMO], 1u); break; } } } } while (0)
; __device__ __forceinline__ void xcd_barrier(const XcdBarrier& b) {
;     ...
;         if (old + 1u == (gen + 1u) * nloc) {
;             __builtin_amdgcn_fence(__ATOMIC_RELEASE, "agent");
;             asm volatile("s_waitcnt vmcnt(0)" ::: "memory");
;             if (nx > 1u) {
;             const unsigned og = xb_add(&bar[XB_TOP], 1u);
;             const unsigned tg = og / nx;
;             if (og + 1u == (tg + 1u) * nx) xb_add(&bar[XB_TOPGEN], 1u);
;             else XB_SPIN(xb_ld(&bar[XB_TOPGEN]) == tg, bar);
;             }
;             __builtin_amdgcn_fence(__ATOMIC_ACQUIRE, "agent");
;             xb_add(&bar[XB_XGEN(b.x)], 1u);
;             asm volatile("s_waitcnt vmcnt(0)" ::: "memory");
.Lnowb_15:
	s_waitcnt vmcnt(0)
	s_cbranch_vccnz .LBB0_1301
	s_mov_b64 s[10:11], exec
	v_mbcnt_lo_u32_b32 v1, s10, 0
	v_mbcnt_hi_u32_b32 v1, s11, v1
	v_cmp_eq_u32_e32 vcc, 0, v1
	s_and_saveexec_b64 s[8:9], vcc
	s_cbranch_execz .LBB0_1286
	s_bcnt1_i32_b64 s10, s[10:11]
	v_mov_b32_e32 v3, s10
	v_mov_b32_e32 v4, 0xa000
	global_atomic_add v3, v4, v3, s[6:7] offset:2560 sc0

; __device__ __forceinline__ unsigned xb_ld(unsigned* p)              { return __hip_atomic_load((GAS unsigned*)p, __ATOMIC_RELAXED, __HIP_MEMORY_SCOPE_AGENT); }
; __device__ __forceinline__ unsigned xb_add(unsigned* p, unsigned v) { return __hip_atomic_fetch_add((GAS unsigned*)p, v, __ATOMIC_RELAXED, __HIP_MEMORY_SCOPE_AGENT); }
; #define XB_SPIN(cond, bar) do { unsigned _sp = 0; while (cond) { __builtin_amdgcn_s_sleep(1); \
;     if ((++_sp & 255u) == 0u) { if (xb_ld(&(bar)[XB_TMO])) break; if (_sp > XB_SPIN_CAP) { xb_add(&(bar)[XB_TMO], 1u); break; } } } } while (0)
; __device__ __forceinline__ void xcd_barrier(const XcdBarrier& b) {
;     ...
;         if (old + 1u == (gen + 1u) * nloc) {
;             __builtin_amdgcn_fence(__ATOMIC_RELEASE, "agent");
;             asm volatile("s_waitcnt vmcnt(0)" ::: "memory");
;             if (nx > 1u) {
;             const unsigned og = xb_add(&bar[XB_TOP], 1u);
;             const unsigned tg = og / nx;
;             if (og + 1u == (tg + 1u) * nx) xb_add(&bar[XB_TOPGEN], 1u);
;             else XB_SPIN(xb_ld(&bar[XB_TOPGEN]) == tg, bar);
;             }
;             __builtin_amdgcn_fence(__ATOMIC_ACQUIRE, "agent");
;             xb_add(&bar[XB_XGEN(b.x)], 1u);
;             asm volatile("s_waitcnt vmcnt(0)" ::: "memory");
.Lnowb_16:
	s_waitcnt vmcnt(0)
	s_cbranch_vccnz .LBB0_1424
	s_mov_b64 s[12:13], exec
	v_mbcnt_lo_u32_b32 v3, s12, 0
	v_mbcnt_hi_u32_b32 v3, s13, v3
	v_cmp_eq_u32_e32 vcc, 0, v3
	s_and_saveexec_b64 s[10:11], vcc
	s_cbranch_execz .LBB0_1409
	s_bcnt1_i32_b64 s12, s[12:13]
	v_mov_b32_e32 v4, s12
	v_mov_b32_e32 v5, 0x7000
	global_atomic_add v4, v5, v4, s[6:7] offset:1024 sc0

; __device__ __forceinline__ unsigned xb_ld(unsigned* p)              { return __hip_atomic_load((GAS unsigned*)p, __ATOMIC_RELAXED, __HIP_MEMORY_SCOPE_AGENT); }
; __device__ __forceinline__ unsigned xb_add(unsigned* p, unsigned v) { return __hip_atomic_fetch_add((GAS unsigned*)p, v, __ATOMIC_RELAXED, __HIP_MEMORY_SCOPE_AGENT); }
; #define XB_SPIN(cond, bar) do { unsigned _sp = 0; while (cond) { __builtin_amdgcn_s_sleep(1); \
;     if ((++_sp & 255u) == 0u) { if (xb_ld(&(bar)[XB_TMO])) break; if (_sp > XB_SPIN_CAP) { xb_add(&(bar)[XB_TMO], 1u); break; } } } } while (0)
; __device__ __forceinline__ void xcd_barrier(const XcdBarrier& b) {
;     ...
;         if (old + 1u == (gen + 1u) * nloc) {
;             __builtin_amdgcn_fence(__ATOMIC_RELEASE, "agent");
;             asm volatile("s_waitcnt vmcnt(0)" ::: "memory");
;             if (nx > 1u) {
;             const unsigned og = xb_add(&bar[XB_TOP], 1u);
;             const unsigned tg = og / nx;
;             if (og + 1u == (tg + 1u) * nx) xb_add(&bar[XB_TOPGEN], 1u);
;             else XB_SPIN(xb_ld(&bar[XB_TOPGEN]) == tg, bar);
;             }
;             __builtin_amdgcn_fence(__ATOMIC_ACQUIRE, "agent");
;             xb_add(&bar[XB_XGEN(b.x)], 1u);
;             asm volatile("s_waitcnt vmcnt(0)" ::: "memory");
.Lnowb_17:
	s_waitcnt vmcnt(0)
	s_cbranch_vccnz .LBB0_1482
	s_mov_b64 s[40:41], exec
	v_mbcnt_lo_u32_b32 v3, s40, 0
	v_mbcnt_hi_u32_b32 v3, s41, v3
	v_cmp_eq_u32_e32 vcc, 0, v3
	s_and_saveexec_b64 s[12:13], vcc
	s_cbranch_execz .LBB0_1467
	s_bcnt1_i32_b64 s20, s[40:41]
	v_mov_b32_e32 v4, s20
	v_mov_b32_e32 v5, 0xa000
	global_atomic_add v4, v5, v4, s[10:11] offset:2560 sc0

; __device__ __forceinline__ unsigned xb_ld(unsigned* p)              { return __hip_atomic_load((GAS unsigned*)p, __ATOMIC_RELAXED, __HIP_MEMORY_SCOPE_AGENT); }
; __device__ __forceinline__ unsigned xb_add(unsigned* p, unsigned v) { return __hip_atomic_fetch_add((GAS unsigned*)p, v, __ATOMIC_RELAXED, __HIP_MEMORY_SCOPE_AGENT); }
; #define XB_SPIN(cond, bar) do { unsigned _sp = 0; while (cond) { __builtin_amdgcn_s_sleep(1); \
;     if ((++_sp & 255u) == 0u) { if (xb_ld(&(bar)[XB_TMO])) break; if (_sp > XB_SPIN_CAP) { xb_add(&(bar)[XB_TMO], 1u); break; } } } } while (0)
; __device__ __forceinline__ void xcd_barrier(const XcdBarrier& b) {
;     ...
;         if (old + 1u == (gen + 1u) * nloc) {
;             __builtin_amdgcn_fence(__ATOMIC_RELEASE, "agent");
;             asm volatile("s_waitcnt vmcnt(0)" ::: "memory");
;             if (nx > 1u) {
;             const unsigned og = xb_add(&bar[XB_TOP], 1u);
;             const unsigned tg = og / nx;
;             if (og + 1u == (tg + 1u) * nx) xb_add(&bar[XB_TOPGEN], 1u);
;             else XB_SPIN(xb_ld(&bar[XB_TOPGEN]) == tg, bar);
;             }
;             __builtin_amdgcn_fence(__ATOMIC_ACQUIRE, "agent");
;             xb_add(&bar[XB_XGEN(b.x)], 1u);
;             asm volatile("s_waitcnt vmcnt(0)" ::: "memory");
.Lnowb_20:
	s_waitcnt vmcnt(0)
	s_cbranch_vccnz .LBB0_1831
	s_mov_b64 s[8:9], exec
	v_mbcnt_lo_u32_b32 v1, s8, 0
	v_mbcnt_hi_u32_b32 v1, s9, v1
	v_cmp_eq_u32_e32 vcc, 0, v1
	s_and_saveexec_b64 s[6:7], vcc
	s_cbranch_execz .LBB0_1816
	s_bcnt1_i32_b64 s8, s[8:9]
	v_mov_b32_e32 v3, s8
	v_mov_b32_e32 v4, 0x7000
	global_atomic_add v3, v4, v3, s[4:5] offset:1024 sc0
